# post phase: GLA chunk-summary unit assignment rotated by G/2 (fifth unit lands on workgroups without the other extra post-phase units)
# baseline (speedup 1.0000x reference)
; DI void phase_post(LAS unsigned char* lds, int l, bool do_qk) {
;     ...
;     for (int u = bx; u < NB * 4 * NCH; u += G) { const int c = u % NCH, h = (u / NCH) & 3, b = u / (4 * NCH); gla_g1_unit(lds, l, b, h, c); }
.LBB0_337:
	s_lshr_b32 s4, s23, 1
	s_add_i32 s24, s24, s4
	s_sub_i32 s4, s24, s23
	s_cmp_ge_i32 s24, s23
	s_cselect_b32 s24, s4, s24
	s_cmpk_gt_i32 s24, 0x41f
	s_cbranch_scc1 .LBB0_364
	s_lshl_b32 s20, s64, 1
